# static s_setprio 1 for waves 4-7 inside the prompt attention loop (reset after the unit), on top of v18
# speedup vs baseline: 1.0007x; 1.0007x over previous
; #define LAS __attribute__((address_space(3)))
; #define GAS __attribute__((address_space(1)))
; #define ATT_ISSUE(t) do { const int trow_ = (sample && (t) == 32) ? kvnew : kv0 + 64 * (t); \
;         _Pragma("unroll") for (int i_ = 0; i_ < 3; ++i_) kreg[i_] = *(const GAS u32x4*)(kb[i_] + (size_t)trow_ * ks[i_]); \
;         _Pragma("unroll") for (int i_ = 0; i_ < 2; ++i_) vreg[i_] = *(const GAS u32x4*)(vb[i_] + (size_t)trow_ * 2); } while (0)
; __device__ __forceinline__ void unit(LAS unsigned char* lds, const Tensors& T, int h, int qrow0, int nact, bool sample, int limbase, int kv0, int kvnew, int nt) {
;     ...
;     const int tid = tid_, lane = tid & 63, r32 = lane & 31, hi = lane >> 5; const int wid = __builtin_amdgcn_readfirstlane(tid >> 6);
;     const bool active = wid < nact;
;     const int lim = sample ? limbase : limbase + (wid >> 1);
;     const char* kb[3]; int ks[3]; unsigned kd[3];
; #pragma unroll
;     for (int i = 0; i < 3; ++i) { const int c = tid + 512 * i, row = c / 24, cc = c % 24;
;         if (cc < 16) { kb[i] = (const char*)T.KN + ((size_t)row * DM + h * 128 + cc * 8) * 2; ks[i] = DM * 2; }
;         else { kb[i] = (const char*)T.KPE + ((size_t)row * 64 + (cc - 16) * 8) * 2; ks[i] = 64 * 2; }
;         kd[i] = (unsigned)(row * KP + cc * 16); }
;     const char* vb[2]; unsigned vd[2];
; #pragma unroll
;     for (int i = 0; i < 2; ++i) { const int c = tid + 512 * i, drow = c >> 3, cc = c & 7;
;         vb[i] = (const char*)T.VT + ((size_t)(h * 128 + drow) * TA + cc * 8) * 2; vd[i] = (unsigned)(drow * VP + (cc >> 1) * 32 + (cc & 1) * 8); }
;     u32x4 kreg[3], vreg[2];
;     ...
;     ATT_ISSUE(0);
;     bf16x8 qf[12];
;     { const bf16_t* qrow = T.Q + (size_t)(qrow0 + 32 * (active ? wid : 0) + r32) * NQ + h * QKD + hi * 8;
; #pragma unroll
;       for (int d0 = 0; d0 < 12; ++d0) qf[d0] = *(const GAS bf16x8*)(qrow + d0 * 16); }
;     float mrun = -1e30f, lrun = 0.f;
;     f32x16 o[4];
; #pragma unroll
;     for (int d = 0; d < 4; ++d)
; #pragma unroll
;         for (int r = 0; r < 16; ++r) o[d][r] = 0.f;
;     LAS float* scr = (LAS float*)(lds + OFF_SCR + wid * 256);
.LBB0_891:
	v_mov_b32_e32 v214, v206
	s_mov_b32 s0, 0x2aaaaaab
	s_nop 0
	v_mul_hi_i32 v0, v214, s0
	v_lshrrev_b32_e32 v1, 31, v0
	v_ashrrev_i32_e32 v0, 2, v0
	v_add_u32_e32 v6, v0, v1
	v_mul_lo_u32 v0, v6, 24
	v_sub_u32_e32 v18, v214, v0
	v_readfirstlane_b32 s8, v214
	v_cmp_lt_i32_e32 vcc, 15, v18
	v_ashrrev_i32_e32 v7, 31, v6
	s_and_saveexec_b64 s[0:1], vcc
	s_xor_b64 s[0:1], exec, s[0:1]
	v_lshlrev_b64 v[0:1], 7, v[6:7]
	v_lshl_add_u32 v164, v18, 3, v212
	v_lshl_add_u64 v[0:1], s[34:35], 0, v[0:1]
	v_lshl_add_u64 v[0:1], v[164:165], 1, v[0:1]
	s_or_saveexec_b64 s[0:1], s[0:1]
	v_mov_b64_e32 v[2:3], 0x80
	s_xor_b64 exec, exec, s[0:1]
	v_lshlrev_b64 v[0:1], 10, v[6:7]
	v_lshlrev_b32_e32 v2, 3, v18
	v_or_b32_e32 v0, s2, v0
	v_ashrrev_i32_e32 v3, 31, v2
	v_lshl_add_u64 v[0:1], v[0:1], 0, v[2:3]
	v_lshl_add_u64 v[0:1], v[0:1], 1, s[64:65]
	v_mov_b64_e32 v[2:3], 0x800
	s_or_b64 exec, exec, s[0:1]
	v_add_u32_e32 v7, 0x200, v214
	s_mov_b32 s0, 0x2aaaaaab
	v_mul_hi_i32 v3, v7, s0
	v_lshrrev_b32_e32 v4, 31, v3
	v_ashrrev_i32_e32 v3, 2, v3
	v_add_u32_e32 v12, v3, v4
	v_mul_lo_u32 v3, v12, 24
	v_sub_u32_e32 v3, v7, v3
	v_cmp_lt_i32_e32 vcc, 15, v3
	v_ashrrev_i32_e32 v13, 31, v12
	s_and_saveexec_b64 s[0:1], vcc
	s_xor_b64 s[0:1], exec, s[0:1]
	v_lshlrev_b64 v[4:5], 7, v[12:13]
	v_lshl_add_u32 v164, v3, 3, v212
	v_lshl_add_u64 v[4:5], s[34:35], 0, v[4:5]
	v_lshl_add_u64 v[4:5], v[164:165], 1, v[4:5]
	s_or_saveexec_b64 s[0:1], s[0:1]
	v_mov_b64_e32 v[8:9], 0x80
	s_xor_b64 exec, exec, s[0:1]
	v_lshlrev_b64 v[4:5], 10, v[12:13]
	v_lshlrev_b32_e32 v8, 3, v3
	v_or_b32_e32 v4, s2, v4
	v_ashrrev_i32_e32 v9, 31, v8
	v_lshl_add_u64 v[4:5], v[4:5], 0, v[8:9]
	v_lshl_add_u64 v[4:5], v[4:5], 1, s[64:65]
	v_mov_b64_e32 v[8:9], 0x800
	s_or_b64 exec, exec, s[0:1]
	v_add_u32_e32 v9, 0x400, v214
	s_mov_b32 s0, 0x2aaaaaab
	v_mul_hi_i32 v10, v9, s0
	v_lshrrev_b32_e32 v11, 31, v10
	v_ashrrev_i32_e32 v10, 2, v10
	v_add_u32_e32 v16, v10, v11
	v_mul_lo_u32 v10, v16, 24
	v_sub_u32_e32 v9, v9, v10
	v_cmp_lt_i32_e32 vcc, 15, v9
	v_ashrrev_i32_e32 v17, 31, v16
	s_and_saveexec_b64 s[0:1], vcc
	s_xor_b64 s[0:1], exec, s[0:1]
	v_lshlrev_b64 v[10:11], 7, v[16:17]
	v_lshl_add_u32 v164, v9, 3, v212
	v_lshl_add_u64 v[10:11], s[34:35], 0, v[10:11]
	v_lshl_add_u64 v[10:11], v[164:165], 1, v[10:11]
	s_or_saveexec_b64 s[0:1], s[0:1]
	v_mov_b64_e32 v[14:15], 0x80
	s_xor_b64 exec, exec, s[0:1]
	v_lshlrev_b64 v[10:11], 10, v[16:17]
	v_lshlrev_b32_e32 v14, 3, v9
	v_or_b32_e32 v10, s2, v10
	v_ashrrev_i32_e32 v15, 31, v14
	v_lshl_add_u64 v[10:11], v[10:11], 0, v[14:15]
	v_lshl_add_u64 v[10:11], v[10:11], 1, s[64:65]
	v_mov_b64_e32 v[14:15], 0x800
	s_or_b64 exec, exec, s[0:1]
	s_lshr_b32 s0, s47, 4
	s_and_b32 s0, s0, 15
	s_lshl_b32 s29, s27, 8
	s_lshl_b32 s1, s0, 11
	s_add_i32 s4, s29, s3
	s_lshl_b32 s5, s27, 2
	s_ashr_i32 s48, s8, 6
	s_ashr_i32 s8, s8, 7
	s_or_b32 s16, s1, 64
	s_lshl_b32 s94, s0, 12
	v_ashrrev_i32_e32 v17, 3, v214
	v_ashrrev_i32_e32 v40, 3, v7
	s_cmp_lt_i32 s48, 8
	v_and_b32_e32 v13, 7, v214
	v_add_u32_e32 v19, s2, v17
	s_mov_b32 s1, 0x10400
	v_add_u32_e32 v41, s2, v40
	s_cselect_b64 s[40:41], -1, 0
	s_lshl_b32 s0, s28, 12
	v_lshlrev_b32_e32 v15, 3, v13
	v_mad_i64_i32 v[20:21], s[12:13], v19, s1, 0
	v_mad_i64_i32 v[36:37], s[12:13], v41, s1, 0
	s_lshl_b32 s27, s48, 5
	v_or_b32_e32 v20, v20, v15
	v_or_b32_e32 v36, v36, v15
	s_movk_i32 s9, 0x190
	s_cmp_gt_i32 s48, 7
	v_lshl_add_u64 v[32:33], v[20:21], 1, s[66:67]
	s_mov_b32 s1, s95
	v_lshl_add_u64 v[36:37], v[36:37], 1, s[66:67]
	v_mul_lo_u32 v7, v12, s9
	s_cselect_b64 s[22:23], -1, 0
	v_lshl_add_u64 v[32:33], v[32:33], 0, s[0:1]
	v_lshl_add_u64 v[36:37], v[36:37], 0, s[0:1]
	v_lshl_add_u32 v218, v3, 4, v7
	v_mul_lo_u32 v3, v6, s9
	v_and_b32_e32 v216, 31, v214
	s_and_b64 s[0:1], s[22:23], exec
	v_lshl_add_u32 v219, v18, 4, v3
	s_cselect_b32 s0, 0, s27
	v_or_b32_e32 v3, s4, v216
	v_add_u32_e32 v3, s0, v3
	v_mov_b64_e32 v[6:7], s[6:7]
	s_movk_i32 s0, 0xc00
	v_mad_i64_i32 v[6:7], s[0:1], v3, s0, v[6:7]
	v_mad_u64_u32 v[20:21], s[12:13], v2, s3, v[0:1]
	v_bfe_u32 v215, v214, 5, 1
	s_mul_i32 s0, s26, 0x180
	s_mov_b32 s1, s95
	global_load_dwordx4 v[20:23], v[20:21], off
	v_mad_u64_u32 v[24:25], s[12:13], v8, s3, v[4:5]
	v_lshl_add_u64 v[6:7], v[6:7], 0, s[0:1]
	v_lshlrev_b32_e32 v186, 4, v215
	v_mov_b32_e32 v187, v165
	global_load_dwordx4 v[24:27], v[24:25], off
	v_mad_u64_u32 v[28:29], s[12:13], v14, s3, v[10:11]
	v_lshl_add_u64 v[6:7], v[6:7], 0, v[186:187]
	global_load_dwordx4 v[28:31], v[28:29], off
	v_mul_lo_u32 v3, v16, s9
	global_load_dwordx4 v[32:35], v[32:33], off
	v_lshl_add_u32 v220, v9, 4, v3
	global_load_dwordx4 v[36:39], v[36:37], off
	s_nop 0
	global_load_dwordx4 v[140:143], v[6:7], off
	global_load_dwordx4 v[136:139], v[6:7], off offset:32
	global_load_dwordx4 v[132:135], v[6:7], off offset:64
	global_load_dwordx4 v[128:131], v[6:7], off offset:96
	global_load_dwordx4 v[124:127], v[6:7], off offset:128
	global_load_dwordx4 v[120:123], v[6:7], off offset:160
	global_load_dwordx4 v[116:119], v[6:7], off offset:192
	global_load_dwordx4 v[112:115], v[6:7], off offset:224
	global_load_dwordx4 v[108:111], v[6:7], off offset:256
	global_load_dwordx4 v[104:107], v[6:7], off offset:288
	global_load_dwordx4 v[100:103], v[6:7], off offset:320
	global_load_dwordx4 v[96:99], v[6:7], off offset:352
	v_lshlrev_b32_e32 v3, 3, v214
	v_lshlrev_b32_e32 v7, 4, v13
	v_and_b32_e32 v3, 8, v3
	s_movk_i32 s0, 0x60
	v_and_or_b32 v6, v7, s0, v3
	v_add_u32_e32 v3, 0, v219
	s_movk_i32 s4, 0x90
	v_mad_u64_u32 v[188:189], s[0:1], v17, s4, v[6:7]
	v_mad_u64_u32 v[190:191], s[0:1], v40, s4, v[6:7]
	s_lshl_b32 s0, s48, 8
	s_add_i32 s12, s0, 0
	v_mad_u64_u32 v[198:199], s[0:1], v2, s16, v[0:1]
	v_mov_b64_e32 v[0:1], s[94:95]
	s_mov_b32 s4, 0x20800
	v_lshlrev_b32_e32 v200, 6, v2
	v_mad_u64_u32 v[192:193], s[0:1], v14, s16, v[10:11]
	v_lshlrev_b32_e32 v164, 6, v14
	v_mov_b32_e32 v14, v165
	v_mov_b32_e32 v15, v165
	v_and_b32_e32 v187, 63, v214
	s_add_i32 s12, s12, 0x15800
	v_mad_u64_u32 v[194:195], s[0:1], v8, s16, v[4:5]
	v_lshlrev_b32_e32 v196, 6, v8
	v_mov_b32_e32 v4, v165
	v_mov_b32_e32 v5, v165
	v_mov_b32_e32 v6, v165
	v_mov_b32_e32 v8, v165
	v_mov_b32_e32 v9, v165
	v_mov_b32_e32 v10, v165
	v_mov_b32_e32 v11, v165
	v_mov_b32_e32 v12, v165
	v_mov_b32_e32 v13, v165
	s_mov_b32 s9, 0
	s_add_i32 s10, s8, s5
	v_cmp_gt_u32_e64 s[38:39], 32, v187
	v_lshl_add_u32 v189, v216, 2, s12
	s_or_b32 s13, s5, 3
	v_mov_b32_e32 v197, v165
	v_mov_b32_e32 v201, v165
	v_mov_b32_e32 v223, 0xf149f2ca
	v_mov_b32_e32 v191, 0
	s_waitcnt vmcnt(0)
; #define ATT_WRITE(buf) do { _Pragma("unroll") for (int i_ = 0; i_ < 3; ++i_) *(LAS u32x4*)(lds + OFF_K + (buf) * KBUF + kd[i_]) = kreg[i_]; \
;         _Pragma("unroll") for (int i_ = 0; i_ < 2; ++i_) { LAS u32x2* d_ = (LAS u32x2*)(lds + OFF_V + (buf) * VBUF + vd[i_]); d_[0] = (u32x2){vreg[i_].x, vreg[i_].y}; d_[2] = (u32x2){vreg[i_].z, vreg[i_].w}; } } while (0)
; __device__ __forceinline__ void unit(LAS unsigned char* lds, const Tensors& T, int h, int qrow0, int nact, bool sample, int limbase, int kv0, int kvnew, int nt) {
;     ...
;     ATT_WRITE(0);
;     __syncthreads();
	ds_write_b128 v3, v[20:23]
	v_add_u32_e32 v3, 0, v218
	ds_write_b128 v3, v[24:27]
	v_add_u32_e32 v3, 0, v220
	ds_write_b128 v3, v[28:31]
	v_add_u32_e32 v3, 0, v188
	v_add_u32_e32 v3, 0xc800, v3
	ds_write2_b64 v3, v[32:33], v[34:35] offset1:2
	v_add_u32_e32 v3, 0, v190
	v_add_u32_e32 v3, 0xc800, v3
	ds_write2_b64 v3, v[36:37], v[38:39] offset1:2
	v_mul_u32_u24_e32 v3, 0x190, v216
	v_add3_u32 v221, 0, v3, v186
	v_lshlrev_b32_e32 v3, 8, v216
	v_sub_u32_e32 v217, v221, v3
	v_mad_i64_i32 v[2:3], s[0:1], v41, s4, v[0:1]
	v_mad_i64_i32 v[0:1], s[0:1], v19, s4, v[0:1]
	v_or_b32_e32 v2, v2, v7
	v_or_b32_e32 v0, v0, v7
	v_lshl_add_u64 v[202:203], s[74:75], 0, v[2:3]
	v_lshl_add_u64 v[204:205], s[74:75], 0, v[0:1]
	v_mov_b32_e32 v0, v165
	v_mov_b32_e32 v1, v165
	v_mov_b32_e32 v2, v165
	v_mov_b32_e32 v3, v165
	v_mov_b32_e32 v7, v165
	v_mov_b64_e32 v[62:63], v[14:15]
	v_mov_b64_e32 v[46:47], v[14:15]
	v_mov_b64_e32 v[30:31], v[14:15]
	v_mov_b64_e32 v[60:61], v[12:13]
	v_mov_b64_e32 v[58:59], v[10:11]
	v_mov_b64_e32 v[56:57], v[8:9]
	v_mov_b64_e32 v[54:55], v[6:7]
	v_mov_b64_e32 v[52:53], v[4:5]
	v_mov_b64_e32 v[50:51], v[2:3]
	v_mov_b64_e32 v[48:49], v[0:1]
	v_mov_b64_e32 v[44:45], v[12:13]
	v_mov_b64_e32 v[42:43], v[10:11]
	v_mov_b64_e32 v[40:41], v[8:9]
	v_mov_b64_e32 v[38:39], v[6:7]
	v_mov_b64_e32 v[36:37], v[4:5]
	v_mov_b64_e32 v[34:35], v[2:3]
	v_mov_b64_e32 v[32:33], v[0:1]
	v_mov_b64_e32 v[28:29], v[12:13]
	v_mov_b64_e32 v[26:27], v[10:11]
	v_mov_b64_e32 v[24:25], v[8:9]
	v_mov_b64_e32 v[22:23], v[6:7]
	v_mov_b64_e32 v[20:21], v[4:5]
	v_mov_b64_e32 v[18:19], v[2:3]
	v_mov_b64_e32 v[16:17], v[0:1]
	s_waitcnt lgkmcnt(0)
	s_barrier
	v_readfirstlane_b32 s0, v206
	s_nop 3
	s_cmp_lt_u32 s0, 0x100
	s_cbranch_scc1 .Lat_prio
	s_setprio 1
; #define LAS __attribute__((address_space(3)))
; __device__ __forceinline__ int crow(int r, int hi) { return (r & 3) + 8 * (r >> 2) + 4 * hi; }
; #define MFMA32(a, b, c) __builtin_amdgcn_mfma_f32_32x32x16_bf16((a), (b), (c), 0, 0, 0)
; __device__ __forceinline__ void unit(LAS unsigned char* lds, const Tensors& T, int h, int qrow0, int nact, bool sample, int limbase, int kv0, int kvnew, int nt) {
;     ...
;         if (t + 1 < nt) ATT_ISSUE(t + 1);
;         if (active && t <= lim) {
;             const LAS unsigned char* kp = lds + OFF_K + buf * KBUF + r32 * KP + hi * 16;
;             f32x16 p0, p1;
; #pragma unroll
;             for (int r = 0; r < 16; ++r) { p0[r] = 0.f; p1[r] = 0.f; }
;             { bf16x8 kf[4][2];
; #pragma unroll
;               for (int i = 0; i < 4; ++i) { kf[i][0] = *(const LAS bf16x8*)(kp + i * 32); kf[i][1] = *(const LAS bf16x8*)(kp + 32 * KP + i * 32); }
;               __builtin_amdgcn_sched_barrier(0);
; #pragma unroll
;               for (int i = 0; i < 12; ++i) {
;                   p0 = MFMA32(kf[i & 3][0], qf[i], p0); p1 = MFMA32(kf[i & 3][1], qf[i], p1);
;                   if (i + 4 < 12) { kf[i & 3][0] = *(const LAS bf16x8*)(kp + (i + 4) * 32); kf[i & 3][1] = *(const LAS bf16x8*)(kp + 32 * KP + (i + 4) * 32); }
;                   __builtin_amdgcn_sched_barrier(0);
;               } }
;             float rm = fmaxf(p0[0], p1[0]);
; #pragma unroll
;             for (int r = 1; r < 16; ++r) rm = fmaxf(rm, fmaxf(p0[r], p1[r]));
;             { const auto rr = __builtin_amdgcn_permlane32_swap(__float_as_uint(rm), __float_as_uint(rm), false, false);
;               rm = fmaxf(__uint_as_float(rr[0]), __uint_as_float(rr[1])); }
;             const bool need = rm > mrun + 8.0f;
;             if (__builtin_amdgcn_ballot_w64(need) != 0ull) {
;                 const float mn = need ? rm : mrun; const float alpha = __builtin_amdgcn_exp2f(mrun - mn); mrun = mn; lrun *= alpha;
;                 if (hi == 0) scr[r32] = alpha;
;                 asm volatile("s_waitcnt lgkmcnt(0)" ::: "memory");
; #pragma unroll
;                 for (int r = 0; r < 16; ++r) { const float f = scr[crow(r, hi)];
; #pragma unroll
;                     for (int d = 0; d < 4; ++d) o[d][r] *= f; }
;                 asm volatile("s_waitcnt lgkmcnt(0)" ::: "memory");
;             }
.Lat_prio:
.LBB0_904:
	global_load_dwordx4 v[160:163], v[198:199], off
	global_load_dwordx4 v[156:159], v[194:195], off
	global_load_dwordx4 v[152:155], v[192:193], off
	global_load_dwordx4 v[148:151], v[204:205], off
	global_load_dwordx4 v[144:147], v[202:203], off
	s_and_b32 s16, s9, 1
	s_cmp_gt_i32 s9, s10
	s_cselect_b64 s[0:1], -1, 0
	s_or_b64 s[0:1], s[22:23], s[0:1]
	s_and_b64 vcc, exec, s[0:1]
	s_cbranch_vccnz .LBB0_909
	s_mul_i32 s0, s16, 0x6400
	v_add_u32_e32 v222, s0, v221
	ds_read_b128 v[64:67], v222
	ds_read_b128 v[224:227], v222 offset:32
	ds_read_b128 v[68:71], v222 offset:12800
	ds_read_b128 v[228:231], v222 offset:12832
	ds_read_b128 v[232:235], v222 offset:64
	ds_read_b128 v[236:239], v222 offset:96
	ds_read_b128 v[240:243], v222 offset:12864
	ds_read_b128 v[244:247], v222 offset:12896
	s_waitcnt lgkmcnt(7)
	v_mfma_f32_32x32x16_bf16 v[80:95], v[64:67], v[140:143], 0
	ds_read_b128 v[248:251], v222 offset:128
	ds_read_b128 v[166:169], v222 offset:12928
	s_waitcnt lgkmcnt(7)
	v_mfma_f32_32x32x16_bf16 v[64:79], v[68:71], v[140:143], 0
	v_mfma_f32_32x32x16_bf16 v[80:95], v[224:227], v[136:139], v[80:95]
	s_waitcnt lgkmcnt(6)
	v_mfma_f32_32x32x16_bf16 v[64:79], v[228:231], v[136:139], v[64:79]
	ds_read_b128 v[224:227], v222 offset:160
	ds_read_b128 v[228:231], v222 offset:12960
	s_waitcnt lgkmcnt(7)
	v_mfma_f32_32x32x16_bf16 v[80:95], v[232:235], v[132:135], v[80:95]
	s_waitcnt lgkmcnt(5)
	v_mfma_f32_32x32x16_bf16 v[64:79], v[240:243], v[132:135], v[64:79]
	ds_read_b128 v[232:235], v222 offset:192
	ds_read_b128 v[240:243], v222 offset:12992
	v_mfma_f32_32x32x16_bf16 v[80:95], v[236:239], v[128:131], v[80:95]
	s_waitcnt lgkmcnt(6)
	v_mfma_f32_32x32x16_bf16 v[64:79], v[244:247], v[128:131], v[64:79]
	ds_read_b128 v[236:239], v222 offset:224
	ds_read_b128 v[244:247], v222 offset:13024
	s_waitcnt lgkmcnt(7)
	v_mfma_f32_32x32x16_bf16 v[80:95], v[248:251], v[124:127], v[80:95]
	s_waitcnt lgkmcnt(6)
	v_mfma_f32_32x32x16_bf16 v[64:79], v[166:169], v[124:127], v[64:79]
	ds_read_b128 v[166:169], v222 offset:256
	ds_read_b128 v[248:251], v222 offset:13056
	s_waitcnt lgkmcnt(7)
	v_mfma_f32_32x32x16_bf16 v[80:95], v[224:227], v[120:123], v[80:95]
	s_waitcnt lgkmcnt(6)
	v_mfma_f32_32x32x16_bf16 v[64:79], v[228:231], v[120:123], v[64:79]
	ds_read_b128 v[224:227], v222 offset:288
	ds_read_b128 v[228:231], v222 offset:13088
	s_waitcnt lgkmcnt(7)
	v_mfma_f32_32x32x16_bf16 v[80:95], v[232:235], v[116:119], v[80:95]
	s_waitcnt lgkmcnt(6)
	v_mfma_f32_32x32x16_bf16 v[64:79], v[240:243], v[116:119], v[64:79]
	ds_read_b128 v[232:235], v222 offset:320
	ds_read_b128 v[240:243], v222 offset:13120
	s_waitcnt lgkmcnt(7)
	v_mfma_f32_32x32x16_bf16 v[80:95], v[236:239], v[112:115], v[80:95]
	s_waitcnt lgkmcnt(6)
	v_mfma_f32_32x32x16_bf16 v[64:79], v[244:247], v[112:115], v[64:79]
	ds_read_b128 v[236:239], v222 offset:352
	ds_read_b128 v[244:247], v222 offset:13152
	s_waitcnt lgkmcnt(7)
	v_mfma_f32_32x32x16_bf16 v[80:95], v[166:169], v[108:111], v[80:95]
	s_waitcnt lgkmcnt(6)
	v_mfma_f32_32x32x16_bf16 v[64:79], v[248:251], v[108:111], v[64:79]
	s_waitcnt lgkmcnt(5)
	v_mfma_f32_32x32x16_bf16 v[80:95], v[224:227], v[104:107], v[80:95]
	s_waitcnt lgkmcnt(4)
	v_mfma_f32_32x32x16_bf16 v[64:79], v[228:231], v[104:107], v[64:79]
	s_waitcnt lgkmcnt(3)
	v_mfma_f32_32x32x16_bf16 v[80:95], v[232:235], v[100:103], v[80:95]
	s_waitcnt lgkmcnt(2)
	v_mfma_f32_32x32x16_bf16 v[64:79], v[240:243], v[100:103], v[64:79]
	s_waitcnt lgkmcnt(1)
	v_mfma_f32_32x32x16_bf16 v[80:95], v[236:239], v[96:99], v[80:95]
	s_waitcnt lgkmcnt(0)
	v_mfma_f32_32x32x16_bf16 v[64:79], v[244:247], v[96:99], v[64:79]
	s_nop 11
	v_max_f32_e32 v166, v81, v65
	v_max_f32_e32 v167, v82, v66
	v_max3_f32 v166, v80, v64, v166
	v_max_f32_e32 v168, v83, v67
	v_max3_f32 v166, v166, v167, v168
	v_max_f32_e32 v167, v84, v68
	v_max_f32_e32 v168, v85, v69
	v_max3_f32 v166, v166, v167, v168
	v_max_f32_e32 v167, v86, v70
	v_max_f32_e32 v168, v87, v71
	v_max3_f32 v166, v166, v167, v168
	v_max_f32_e32 v167, v88, v72
	v_max_f32_e32 v168, v89, v73
	v_max3_f32 v166, v166, v167, v168
	v_max_f32_e32 v167, v90, v74
	v_max_f32_e32 v168, v91, v75
	v_max3_f32 v166, v166, v167, v168
	v_max_f32_e32 v167, v92, v76
	v_max_f32_e32 v168, v93, v77
	v_max3_f32 v166, v166, v167, v168
	v_max_f32_e32 v167, v94, v78
	v_max_f32_e32 v168, v95, v79
	v_max3_f32 v166, v166, v167, v168
	v_mov_b32_e32 v167, v166
	s_nop 1
	v_permlane32_swap_b32_e32 v166, v167
	v_max_f32_e32 v222, v166, v167
	v_add_f32_e32 v166, 0x41000000, v223
	v_cmp_gt_f32_e32 vcc, v222, v166
	s_cbranch_vccz .LBB0_910
	s_nop 0
	v_cndmask_b32_e32 v222, v223, v222, vcc
	v_sub_f32_e32 v166, v223, v222
	v_exp_f32_e32 v223, v166
	s_and_saveexec_b64 s[0:1], s[38:39]
	ds_write_b32 v189, v223
	s_or_b64 exec, exec, s[0:1]
	v_mul_f32_e32 v191, v191, v223
	s_waitcnt lgkmcnt(0)
	v_add_u32_e32 v223, s12, v186
	ds_read_b128 v[166:169], v223
	ds_read_b128 v[224:227], v223 offset:32
	ds_read_b128 v[228:231], v223 offset:64
	ds_read_b128 v[232:235], v223 offset:96
	s_waitcnt lgkmcnt(0)
	s_waitcnt lgkmcnt(3)
	v_pk_mul_f32 v[2:3], v[2:3], v[168:169]
	s_waitcnt lgkmcnt(2)
	v_pk_mul_f32 v[4:5], v[4:5], v[224:225]
	s_waitcnt lgkmcnt(1)
	v_pk_mul_f32 v[8:9], v[8:9], v[228:229]
	s_waitcnt lgkmcnt(0)
	v_pk_mul_f32 v[12:13], v[12:13], v[232:233]
	v_pk_mul_f32 v[14:15], v[14:15], v[234:235]
	v_pk_mul_f32 v[10:11], v[10:11], v[230:231]
	v_pk_mul_f32 v[6:7], v[6:7], v[226:227]
	v_pk_mul_f32 v[0:1], v[0:1], v[166:167]
	v_pk_mul_f32 v[60:61], v[60:61], v[232:233]
	v_pk_mul_f32 v[56:57], v[56:57], v[228:229]
	v_pk_mul_f32 v[52:53], v[52:53], v[224:225]
	v_pk_mul_f32 v[62:63], v[62:63], v[234:235]
	v_pk_mul_f32 v[58:59], v[58:59], v[230:231]
	v_pk_mul_f32 v[54:55], v[54:55], v[226:227]
	v_pk_mul_f32 v[50:51], v[50:51], v[168:169]
	v_pk_mul_f32 v[48:49], v[48:49], v[166:167]
	v_pk_mul_f32 v[44:45], v[44:45], v[232:233]
	v_pk_mul_f32 v[40:41], v[40:41], v[228:229]
	v_pk_mul_f32 v[36:37], v[36:37], v[224:225]
	v_pk_mul_f32 v[46:47], v[46:47], v[234:235]
	v_pk_mul_f32 v[42:43], v[42:43], v[230:231]
	v_pk_mul_f32 v[38:39], v[38:39], v[226:227]
	v_pk_mul_f32 v[34:35], v[34:35], v[168:169]
	v_pk_mul_f32 v[32:33], v[32:33], v[166:167]
	v_pk_mul_f32 v[28:29], v[28:29], v[232:233]
	v_pk_mul_f32 v[24:25], v[24:25], v[228:229]
	v_pk_mul_f32 v[20:21], v[20:21], v[224:225]
	v_pk_mul_f32 v[30:31], v[30:31], v[234:235]
	v_pk_mul_f32 v[26:27], v[26:27], v[230:231]
	v_pk_mul_f32 v[22:23], v[22:23], v[226:227]
	v_pk_mul_f32 v[18:19], v[18:19], v[168:169]
	v_pk_mul_f32 v[16:17], v[16:17], v[166:167]
	s_branch .LBB0_911

; __device__ __forceinline__ void unit(LAS unsigned char* lds, const Tensors& T, int h, int qrow0, int nact, bool sample, int limbase, int kv0, int kvnew, int nt) {
;     ...
;         __syncthreads();
;     }
;     if (active) {
;         lrun += __shfl_xor(lrun, 32);
;         if (hi == 0) scr[r32] = __builtin_amdgcn_rcpf(lrun);
.LBB0_926:
	s_and_b64 vcc, exec, s[40:41]
	s_barrier
	s_setprio 0
	s_cbranch_vccz .LBB0_935
	v_and_b32_e32 v65, 64, v213
	v_xor_b32_e32 v64, 32, v213
	v_add_u32_e32 v65, 64, v65
	v_cmp_lt_i32_e32 vcc, v64, v65
	s_nop 1
	v_cndmask_b32_e32 v64, v213, v64, vcc
	v_lshlrev_b32_e32 v64, 2, v64
	ds_bpermute_b32 v64, v64, v191
	s_and_saveexec_b64 s[0:1], s[38:39]
	s_cbranch_execz .LBB0_929
	s_waitcnt lgkmcnt(0)
	v_add_f32_e32 v64, v191, v64
	v_rcp_f32_e32 v64, v64
	ds_write_b32 v189, v64
